# hand-written symmetric 8-wave RWKV scan phase (all waves run the recurrence, scalar f32 ops, prefetch distance 3)
# baseline (speedup 1.0000x reference)
.LBB0_238:
	s_andn2_b64 vcc, exec, s[4:5]
	s_cbranch_vccnz .LBB0_389
	s_waitcnt lgkmcnt(0)
	s_cmpk_eq_i32 s94, 0x100
	s_cbranch_scc1 .Lsn_entry
	s_add_u32 s62, s22, 0x9d58000
	s_addc_u32 s63, s23, 0
	s_add_u32 s64, s22, 0xbfd8000
	s_addc_u32 s65, s23, 0
	s_add_u32 s66, s22, 0x5858000
	s_addc_u32 s67, s23, 0
	s_add_u32 s68, s22, 0x7ad8000
	s_addc_u32 s69, s23, 0
	s_add_u32 s88, s22, 0x2398000
	s_addc_u32 s89, s23, 0
	s_movk_i32 s2, 0xff
	s_cmpk_lt_i32 s14, 0x1100
	v_add_u32_e32 v45, 0xffffff00, v231
	v_cmp_lt_i32_e64 s[2:3], s2, v231
	s_cselect_b64 s[6:7], -1, 0
	v_ashrrev_i32_e32 v189, 3, v45
	v_and_b32_e32 v44, 7, v231
	s_and_b64 s[4:5], s[6:7], s[2:3]
	s_and_saveexec_b64 s[8:9], s[4:5]
	s_cbranch_execz .LBB0_250
	s_cmpk_lt_i32 s14, 0x100
	s_waitcnt vmcnt(0)
	v_lshrrev_b32_e32 v0, 6, v45
	v_mul_lo_u32 v0, v0, s94
	s_cselect_b64 vcc, -1, 0
	v_cndmask_b32_e64 v0, v0, 0, vcc
	v_add_u32_e32 v0, s14, v0
	s_movk_i32 s4, 0x1100
	v_cmp_gt_i32_e64 s[4:5], s4, v0
	s_and_b64 exec, exec, s[4:5]
	s_cbranch_execz .LBB0_250
	s_movk_i32 s4, 0xff
	v_cmp_lt_i32_e64 s[4:5], s4, v0
	s_and_saveexec_b64 s[10:11], s[4:5]
	s_xor_b64 s[4:5], exec, s[10:11]
	v_add_u32_e32 v1, 0xffffff00, v0
	v_lshrrev_b32_e32 v1, 2, v1
	v_and_b32_e32 v1, 0x3ffffff8, v1
	v_add_u32_e32 v1, 0x4080, v1
	s_or_saveexec_b64 s[4:5], s[4:5]
	v_mov_b32_e32 v2, 8
	s_xor_b64 exec, exec, s[4:5]
	v_ashrrev_i32_e32 v1, 5, v0
	v_mov_b32_e32 v2, 0x810
	v_mul_lo_u32 v1, v1, v2
	s_or_b64 exec, exec, s[4:5]
	v_bfe_u32 v3, v45, 3, 3
	v_cndmask_b32_e32 v3, v3, v189, vcc
	v_cmp_lt_i32_e32 vcc, v3, v2
	s_and_b64 exec, exec, vcc
	s_cbranch_execz .LBB0_250
	v_add_u32_e32 v24, v1, v3
	v_bfe_u32 v46, v0, 1, 4
	v_ashrrev_i32_e32 v25, 31, v24
	v_lshlrev_b64 v[2:3], 10, v[24:25]
	v_lshlrev_b32_e32 v47, 6, v46
	v_lshlrev_b32_e32 v176, 3, v44
	v_or3_b32 v2, v2, v47, v176
	v_lshlrev_b64 v[2:3], 1, v[2:3]
	s_load_dwordx4 s[16:19], s[48:49], 0xa8
	s_waitcnt vmcnt(3)
	v_lshl_add_u64 v[4:5], s[62:63], 0, v[2:3]
	global_load_dwordx4 v[28:31], v[4:5], off
	v_lshl_add_u64 v[4:5], s[64:65], 0, v[2:3]
	global_load_dwordx4 v[12:15], v[4:5], off
	v_lshl_add_u64 v[4:5], s[68:69], 0, v[2:3]
	global_load_dwordx4 v[16:19], v[4:5], off
	v_mov_b32_e32 v5, v177
	v_lshlrev_b32_e32 v4, 8, v46
	v_lshlrev_b32_e32 v6, 5, v44
	v_mov_b32_e32 v7, v177
	s_waitcnt vmcnt(5) lgkmcnt(0)
	v_lshl_add_u64 v[8:9], s[16:17], 0, v[4:5]
	v_lshl_add_u64 v[4:5], s[18:19], 0, v[4:5]
	v_lshl_add_u64 v[8:9], v[8:9], 0, v[6:7]
	v_lshl_add_u64 v[4:5], v[4:5], 0, v[6:7]
	global_load_dwordx4 v[36:39], v[8:9], off
	global_load_dwordx4 v[40:43], v[8:9], off offset:16
	global_load_dwordx4 v[48:51], v[4:5], off
	global_load_dwordx4 v[20:23], v[4:5], off offset:16
	v_lshlrev_b64 v[6:7], 11, v[24:25]
	v_and_b32_e32 v60, 1, v0
	v_mov_b32_e32 v1, v177
	v_lshlrev_b32_e32 v0, 7, v46
	v_lshl_add_u64 v[6:7], s[20:21], 0, v[6:7]
	v_mov_b32_e32 v5, v177
	v_lshlrev_b32_e32 v4, 6, v60
	v_lshl_add_u64 v[0:1], v[6:7], 0, v[0:1]
	v_lshl_add_u64 v[0:1], v[0:1], 0, v[4:5]
	v_lshl_add_u64 v[2:3], s[66:67], 0, v[2:3]
	v_lshl_add_u64 v[0:1], v[0:1], 0, v[176:177]
	global_load_dwordx4 v[8:11], v[2:3], off
	global_load_dwordx2 v[26:27], v[0:1], off
	v_cmp_eq_u32_e32 vcc, 0, v60
	s_waitcnt vmcnt(8)
	v_lshlrev_b32_e32 v0, 16, v30
	v_and_b32_e32 v1, 0xffff0000, v30
	v_lshlrev_b32_e32 v2, 16, v31
	v_and_b32_e32 v3, 0xffff0000, v31
	s_waitcnt vmcnt(7)
	v_lshlrev_b32_e32 v52, 16, v12
	v_and_b32_e32 v53, 0xffff0000, v12
	s_waitcnt vmcnt(6)
	v_lshlrev_b32_e32 v30, 16, v17
	v_and_b32_e32 v31, 0xffff0000, v17
	v_lshlrev_b32_e32 v32, 16, v18
	v_and_b32_e32 v33, 0xffff0000, v18
	v_lshlrev_b32_e32 v4, 16, v28
	v_and_b32_e32 v5, 0xffff0000, v28
	v_lshlrev_b32_e32 v6, 16, v29
	v_and_b32_e32 v7, 0xffff0000, v29
	v_lshlrev_b32_e32 v28, 16, v16
	v_and_b32_e32 v29, 0xffff0000, v16
	v_lshlrev_b32_e32 v12, 16, v13
	v_and_b32_e32 v13, 0xffff0000, v13
	v_lshlrev_b32_e32 v34, 16, v19
	v_and_b32_e32 v35, 0xffff0000, v19
	s_waitcnt vmcnt(5)
	v_pk_mul_f32 v[36:37], v[36:37], v[52:53]
	v_pk_add_f32 v[18:19], v[30:31], -1.0 op_sel_hi:[1,0]
	v_pk_add_f32 v[56:57], v[32:33], -1.0 op_sel_hi:[1,0]
	v_lshlrev_b32_e32 v54, 16, v14
	v_and_b32_e32 v55, 0xffff0000, v14
	v_pk_add_f32 v[16:17], v[28:29], -1.0 op_sel_hi:[1,0]
	v_pk_mul_f32 v[38:39], v[38:39], v[12:13]
	v_pk_mul_f32 v[58:59], v[36:37], v[36:37]
	s_waitcnt vmcnt(3)
	v_pk_fma_f32 v[18:19], v[18:19], v[50:51], 1.0 op_sel_hi:[1,1,0]
	s_waitcnt vmcnt(2)
	v_pk_fma_f32 v[20:21], v[56:57], v[20:21], 1.0 op_sel_hi:[1,1,0]
	v_pk_fma_f32 v[16:17], v[16:17], v[48:49], 1.0 op_sel_hi:[1,1,0]
	v_pk_mul_f32 v[48:49], v[38:39], v[38:39]
	v_pk_mul_f32 v[18:19], v[18:19], v[12:13]
	v_pk_mul_f32 v[12:13], v[20:21], v[54:55]
	v_add_f32_e32 v20, v58, v59
	v_pk_mul_f32 v[40:41], v[40:41], v[54:55]
	v_add_f32_e32 v20, v48, v20
	v_lshlrev_b32_e32 v14, 16, v15
	v_and_b32_e32 v15, 0xffff0000, v15
	v_pk_mul_f32 v[50:51], v[40:41], v[40:41]
	v_add_f32_e32 v20, v49, v20
	v_pk_mul_f32 v[42:43], v[42:43], v[14:15]
	v_add_f32_e32 v20, v50, v20
	v_pk_mul_f32 v[56:57], v[42:43], v[42:43]
	v_add_f32_e32 v20, v51, v20
	v_add_f32_e32 v20, v56, v20
	v_add_f32_e32 v20, v57, v20
	v_pk_add_f32 v[48:49], v[34:35], -1.0 op_sel_hi:[1,0]
	v_pk_mul_f32 v[16:17], v[16:17], v[52:53]
	v_add_f32_dpp v20, v20, v20 quad_perm:[1,0,3,2] row_mask:0xf bank_mask:0xf bound_ctrl:1
	v_pk_fma_f32 v[22:23], v[48:49], v[22:23], 1.0 op_sel_hi:[1,1,0]
	s_nop 0
	v_add_f32_dpp v20, v20, v20 quad_perm:[2,3,0,1] row_mask:0xf bank_mask:0xf bound_ctrl:1
	ds_bpermute_b32 v21, v221, v20
	v_pk_mul_f32 v[14:15], v[22:23], v[14:15]
	s_and_saveexec_b64 s[4:5], vcc
	s_cbranch_execz .LBB0_249
	s_load_dwordx2 s[10:11], s[48:49], 0xb8
	v_lshlrev_b32_e32 v22, 2, v47
	v_mov_b32_e32 v23, v177
	v_lshlrev_b32_e32 v176, 2, v176
	v_mul_f32_e32 v47, v18, v6
	s_waitcnt lgkmcnt(0)
	v_lshl_add_u64 v[22:23], s[10:11], 0, v[22:23]
	v_lshl_add_u64 v[22:23], v[22:23], 0, v[176:177]
	global_load_dwordx4 v[48:51], v[22:23], off
	global_load_dwordx4 v[52:55], v[22:23], off offset:16
	v_mul_f32_e32 v22, v16, v4
	v_mul_f32_e32 v23, v17, v5
	v_mul_f32_e32 v56, v19, v7
	v_mul_f32_e32 v57, v12, v0
	v_mul_f32_e32 v58, v13, v1
	v_mul_f32_e32 v59, v14, v2
	v_cmp_eq_u32_e32 vcc, 0, v44
	s_waitcnt vmcnt(1)
	v_fma_f32 v22, v22, v48, 0
	v_fmac_f32_e32 v22, v23, v49
	v_fmac_f32_e32 v22, v47, v50
	v_fmac_f32_e32 v22, v56, v51
	s_waitcnt vmcnt(0)
	v_fmac_f32_e32 v22, v57, v52
	v_fmac_f32_e32 v22, v58, v53
	v_fmac_f32_e32 v22, v59, v54
	v_mul_f32_e32 v23, v15, v3
	v_fmac_f32_e32 v22, v23, v55
	s_nop 1
	v_add_f32_dpp v22, v22, v22 quad_perm:[1,0,3,2] row_mask:0xf bank_mask:0xf bound_ctrl:1
	s_nop 1
	v_add_f32_dpp v22, v22, v22 quad_perm:[2,3,0,1] row_mask:0xf bank_mask:0xf bound_ctrl:1
	ds_bpermute_b32 v23, v221, v22
	s_and_b64 exec, exec, vcc
	s_cbranch_execz .LBB0_249
	s_waitcnt lgkmcnt(0)
	v_add_f32_e32 v47, v22, v23
	v_lshlrev_b64 v[22:23], 6, v[24:25]
	v_lshl_add_u64 v[22:23], s[88:89], 0, v[22:23]
	v_lshlrev_b32_e32 v176, 2, v46
	v_lshl_add_u64 v[22:23], v[22:23], 0, v[176:177]
	global_store_dword v[22:23], v47, off

.Lsn_entry:
	v_writelane_b32 v175, s50, 0
	v_writelane_b32 v175, s51, 1
	v_writelane_b32 v175, s52, 2
	v_writelane_b32 v175, s53, 3
	v_writelane_b32 v175, s54, 4
	v_writelane_b32 v175, s55, 5
	v_writelane_b32 v175, s56, 6
	v_writelane_b32 v175, s57, 7
	v_writelane_b32 v175, s58, 8
	v_writelane_b32 v175, s59, 9
	v_writelane_b32 v175, s60, 10
	v_writelane_b32 v175, s61, 11
	v_writelane_b32 v175, s62, 12
	v_writelane_b32 v175, s63, 13
	v_writelane_b32 v175, s64, 14
	v_writelane_b32 v175, s65, 15
	v_writelane_b32 v175, s66, 16
	v_writelane_b32 v175, s67, 17
	v_writelane_b32 v175, s68, 18
	v_writelane_b32 v175, s69, 19
	v_writelane_b32 v175, s70, 20
	v_writelane_b32 v175, s71, 21
	v_writelane_b32 v175, s72, 22
	v_writelane_b32 v175, s73, 23
	v_writelane_b32 v175, s74, 24
	v_writelane_b32 v175, s75, 25
	v_writelane_b32 v175, s76, 26
	v_writelane_b32 v175, s77, 27
	v_writelane_b32 v175, s78, 28
	v_writelane_b32 v175, s79, 29
	v_writelane_b32 v175, s80, 30
	v_writelane_b32 v175, s81, 31
	v_writelane_b32 v175, s82, 32
	v_writelane_b32 v175, s83, 33
	v_writelane_b32 v175, s84, 34
	v_writelane_b32 v175, s85, 35
	v_writelane_b32 v175, s86, 36
	v_writelane_b32 v175, s87, 37
	v_writelane_b32 v175, s88, 38
	v_writelane_b32 v175, s89, 39
	v_writelane_b32 v175, s90, 40
	v_writelane_b32 v175, s91, 41
	v_writelane_b32 v175, s92, 42
	v_writelane_b32 v175, s93, 43
	s_add_u32 s50, s22, 0x9d58000
	s_addc_u32 s51, s23, 0
	s_add_u32 s52, s22, 0xbfd8000
	s_addc_u32 s53, s23, 0
	s_add_u32 s54, s22, 0x5858000
	s_addc_u32 s55, s23, 0
	s_add_u32 s56, s22, 0x7ad8000
	s_addc_u32 s57, s23, 0
	s_mov_b64 s[58:59], s[20:21]
	s_add_u32 s60, s20, 0x2280000
	s_addc_u32 s61, s21, 0
	s_add_u32 s62, s22, 0xe499000
	s_addc_u32 s63, s23, 0
	s_add_u32 s64, s22, 0x2398000
	s_addc_u32 s65, s23, 0
	s_add_u32 s68, s20, 0x4618000
	s_addc_u32 s69, s21, 0
	s_add_u32 s70, s20, 0x4400000
	s_addc_u32 s71, s21, 0
	s_load_dwordx2 s[66:67], s[48:49], 0x10
	s_load_dwordx2 s[76:77], s[48:49], 0xa8
	s_load_dwordx2 s[86:87], s[48:49], 0xb0
	s_load_dwordx2 s[92:93], s[48:49], 0xb8
	v_lshrrev_b32_e32 v121, 4, v231
	v_and_b32_e32 v122, 15, v231
	s_lshr_b32 s90, s14, 5
	s_mul_i32 s88, s90, 2064
	s_lshl_b32 s89, s90, 3
	s_add_i32 s89, s89, 16512
	s_lshl_b32 s91, s90, 18
	s_lshr_b32 s90, s14, 1
	s_and_b32 s90, s90, 15
	s_and_b32 s73, s14, 1
	v_and_b32_e32 v8, 1, v122
	v_cmp_ne_u32_e64 s[78:79], 0, v8
	v_and_b32_e32 v8, 2, v122
	v_cmp_ne_u32_e64 s[80:81], 0, v8
	v_cmp_gt_u32_e64 s[82:83], 8, v122
	v_cmp_eq_u32_e64 s[84:85], 0, v122
	s_cmp_eq_u32 s73, 0
	s_cselect_b64 s[74:75], -1, 0
	s_and_b64 s[84:85], s[84:85], s[74:75]
	s_lshl_b32 s74, s90, 7
	s_lshl_b32 s75, s73, 6
	v_lshl_add_u32 v164, v122, 3, s74
	v_and_b32_e32 v8, 7, v122
	s_add_i32 s75, s75, s74
	v_lshl_add_u32 v165, v8, 3, s75
	v_lshl_add_u32 v166, v122, 2, s75
	s_lshl_b32 s74, s90, 14
	s_lshl_b32 s75, s73, 13
	s_add_i32 s74, s74, s75
	s_add_i32 s74, s74, s91
	v_lshlrev_b32_e32 v9, 8, v121
	v_lshl_add_u32 v9, v122, 4, v9
	v_add_u32_e32 v167, s74, v9
	v_lshrrev_b32_e32 v9, 3, v121
	v_and_b32_e32 v10, 7, v121
	v_lshl_add_u32 v168, v9, 6, v10
	v_lshlrev_b32_e32 v171, 4, v122
	v_lshlrev_b32_e32 v9, 7, v121
	v_add_u32_e32 v172, 40960, v9
	v_and_b32_e32 v10, 3, v122
	v_lshlrev_b32_e32 v10, 7, v10
	v_lshl_add_u32 v10, v121, 2, v10
	v_add_u32_e32 v173, 0x16000, v10
	v_lshlrev_b32_e32 v9, 8, v121
	v_lshl_add_u32 v123, v122, 4, v9
	v_lshlrev_b32_e32 v9, 9, v8
	v_lshl_add_u32 v9, v121, 2, v9
	v_add_u32_e32 v124, 40960, v9
	v_lshlrev_b32_e32 v9, 7, v121
	v_lshl_add_u32 v9, v122, 3, v9
	v_add_u32_e32 v125, 0x16000, v9
	s_lshl_b32 s74, s90, 8
	v_lshl_add_u32 v9, v122, 4, s74
	s_waitcnt lgkmcnt(0)
	global_load_dwordx4 v[136:139], v9, s[76:77]
	global_load_dwordx4 v[140:143], v9, s[86:87]
	global_load_dwordx4 v[144:147], v9, s[92:93]
	v_mov_b32_e32 v0, 0
	v_mov_b32_e32 v1, 0
	v_mov_b32_e32 v2, 0
	v_mov_b32_e32 v3, 0
	v_mov_b32_e32 v5, 0
	s_mov_b32 s72, -1
	s_mov_b32 s74, 0
.Lsn_chunk:
	s_add_i32 s75, s72, 1
	s_cmp_ge_i32 s75, 69
	s_cbranch_scc1 .Lsn_noA
	s_cmp_ge_i32 s75, 65
	s_cbranch_scc1 .Lsn_A_sample
	s_lshl_b32 s76, s75, 5
	v_add_u32_e32 v174, s76, v121
	s_movk_i32 s77, 0x810
	v_cmp_gt_u32_e64 s[86:87], s77, v174
	s_add_i32 s76, s76, s88
	v_add_u32_e32 v170, s76, v121
	s_branch .Lsn_A_common
.Lsn_A_sample:
	s_sub_i32 s76, s75, 65
	s_lshl_b32 s77, s76, 8
	s_add_i32 s77, s77, s89
	v_add_u32_e32 v170, s77, v168
	s_mov_b64 s[86:87], -1
	s_lshl_b32 s77, s76, 23
	v_add_u32_e32 v174, s77, v167
	global_load_dwordx4 v[188:191], v174, s[66:67]
	v_add_u32_e32 v174, 0x200000, v174
	global_load_dwordx4 v[192:195], v174, s[66:67]
	v_add_u32_e32 v174, 0x200000, v174
	global_load_dwordx4 v[196:199], v174, s[66:67]
	v_add_u32_e32 v174, 0x200000, v174
	global_load_dwordx4 v[200:203], v174, s[66:67]
.Lsn_A_common:
	v_lshl_add_u32 v174, v170, 11, v164
	global_load_dwordx2 v[126:127], v174, s[52:53]
	global_load_dwordx2 v[128:129], v174, s[50:51]
	global_load_dwordx2 v[130:131], v174, s[56:57]
	global_load_dwordx2 v[132:133], v174, s[54:55]
	v_lshl_add_u32 v174, v170, 11, v165
	global_load_dwordx2 v[134:135], v174, s[58:59]
.Lsn_noA:
	s_cmp_lt_i32 s72, 0
	s_cbranch_scc1 .Lsn_noB
	s_lshl_b32 s76, s72, 5
	s_sub_i32 s76, 0x810, s76
	s_lshr_b32 s76, s76, 3
	s_min_i32 s73, s76, 4
	s_cmp_ge_i32 s72, 65
	s_cselect_b32 s74, 1, 0
	s_cselect_b32 s73, 4, s73
	s_and_b32 s76, s72, 1
	s_mul_i32 s77, s76, 45056
	v_add_u32_e32 v118, s77, v171
	v_add_u32_e32 v119, s77, v172
	s_lshl_b32 s76, s76, 12
	v_add_u32_e32 v120, s76, v173
	s_sub_i32 s76, s72, 65
	s_lshl_b32 s76, s76, 23
	v_add_u32_e32 v169, s76, v167
	ds_read_b128 v[88:91], v119
	ds_read_b128 v[12:15], v118 offset:0
	ds_read_b128 v[8:11], v118 offset:8192
	ds_read_b128 v[16:19], v118 offset:16384
	ds_read_b128 v[20:23], v118 offset:24576
	ds_read_b128 v[24:27], v118 offset:32768
	ds_read_b128 v[32:35], v118 offset:256
	ds_read_b128 v[28:31], v118 offset:8448
	ds_read_b128 v[36:39], v118 offset:16640
	ds_read_b128 v[40:43], v118 offset:24832
	ds_read_b128 v[44:47], v118 offset:33024
	ds_read_b128 v[52:55], v118 offset:512
	ds_read_b128 v[48:51], v118 offset:8704
	ds_read_b128 v[56:59], v118 offset:16896
	ds_read_b128 v[60:63], v118 offset:25088
	ds_read_b128 v[64:67], v118 offset:33280
	s_waitcnt lgkmcnt(10)
.Lsn_iter:
	s_cmp_eq_u32 s74, 1
	s_cbranch_scc0 .Lsn_noswap
	v_mov_b32_e32 v0, v148
	v_mov_b32_e32 v1, v149
	v_mov_b32_e32 v2, v150
	v_mov_b32_e32 v3, v151
	v_mov_b32_e32 v148, v152
	v_mov_b32_e32 v149, v153
	v_mov_b32_e32 v150, v154
	v_mov_b32_e32 v151, v155
	v_mov_b32_e32 v152, v156
	v_mov_b32_e32 v153, v157
	v_mov_b32_e32 v154, v158
	v_mov_b32_e32 v155, v159
	v_mov_b32_e32 v156, v160
	v_mov_b32_e32 v157, v161
	v_mov_b32_e32 v158, v162
	v_mov_b32_e32 v159, v163
.Lsn_noswap:
	s_waitcnt lgkmcnt(12)
	v_mul_f32_e32 v4, v0, v8
	v_mul_f32_e32 v96, v20, v88
	v_fmac_f32_e32 v4, v1, v9
	v_mul_f32_e32 v97, v21, v88
	v_fmac_f32_e32 v4, v2, v10
	v_mul_f32_e32 v98, v22, v88
	v_fmac_f32_e32 v4, v3, v11
	v_mul_f32_e32 v99, v23, v88
	v_fmac_f32_e32 v96, v0, v12
	v_fmac_f32_e32 v97, v1, v13
	v_add_f32_dpp v4, v4, v4 quad_perm:[1,0,3,2] row_mask:0xf bank_mask:0xf bound_ctrl:1
	v_fmac_f32_e32 v98, v2, v14
	v_fmac_f32_e32 v99, v3, v15
	v_add_f32_dpp v4, v4, v4 quad_perm:[2,3,0,1] row_mask:0xf bank_mask:0xf bound_ctrl:1
	ds_read_b128 v[72:75], v118 offset:768
	ds_read_b128 v[68:71], v118 offset:8960
	v_add_f32_dpp v4, v4, v4 row_ror:4 row_mask:0xf bank_mask:0xf bound_ctrl:1
	ds_read_b128 v[76:79], v118 offset:17152
	ds_read_b128 v[80:83], v118 offset:25344
	v_add_f32_dpp v4, v4, v4 row_ror:8 row_mask:0xf bank_mask:0xf bound_ctrl:1
	ds_read_b128 v[84:87], v118 offset:33536
	v_fma_f32 v0, -v16, v4, v96
	v_fma_f32 v1, -v17, v4, v97
	v_fma_f32 v2, -v18, v4, v98
	v_fma_f32 v3, -v19, v4, v99
	v_mul_f32_e32 v102, v0, v24
	v_fmac_f32_e32 v102, v1, v25
	v_fmac_f32_e32 v102, v2, v26
	v_fmac_f32_e32 v102, v3, v27
	s_waitcnt lgkmcnt(10)
	v_mul_f32_e32 v4, v0, v28
	v_mul_f32_e32 v96, v40, v89
	v_fmac_f32_e32 v4, v1, v29
	v_mul_f32_e32 v97, v41, v89
	v_fmac_f32_e32 v4, v2, v30
	v_mul_f32_e32 v98, v42, v89
	v_fmac_f32_e32 v4, v3, v31
	v_mul_f32_e32 v99, v43, v89
	v_fmac_f32_e32 v96, v0, v32
	v_fmac_f32_e32 v97, v1, v33
	v_add_f32_dpp v4, v4, v4 quad_perm:[1,0,3,2] row_mask:0xf bank_mask:0xf bound_ctrl:1
	v_fmac_f32_e32 v98, v2, v34
	v_fmac_f32_e32 v99, v3, v35
	v_add_f32_dpp v4, v4, v4 quad_perm:[2,3,0,1] row_mask:0xf bank_mask:0xf bound_ctrl:1
	ds_read_b128 v[12:15], v118 offset:1024
	ds_read_b128 v[8:11], v118 offset:9216
	v_add_f32_dpp v4, v4, v4 row_ror:4 row_mask:0xf bank_mask:0xf bound_ctrl:1
	ds_read_b128 v[16:19], v118 offset:17408
	ds_read_b128 v[20:23], v118 offset:25600
	v_add_f32_dpp v4, v4, v4 row_ror:8 row_mask:0xf bank_mask:0xf bound_ctrl:1
	ds_read_b128 v[24:27], v118 offset:33792
	ds_read_b128 v[92:95], v119 offset:16
	v_fma_f32 v0, -v36, v4, v96
	v_fma_f32 v1, -v37, v4, v97
	v_fma_f32 v2, -v38, v4, v98
	v_fma_f32 v3, -v39, v4, v99
	v_mul_f32_e32 v103, v0, v44
	v_fmac_f32_e32 v103, v1, v45
	v_fmac_f32_e32 v103, v2, v46
	v_fmac_f32_e32 v103, v3, v47
	s_waitcnt lgkmcnt(11)
	v_mul_f32_e32 v4, v0, v48
	v_mul_f32_e32 v96, v60, v90
	v_fmac_f32_e32 v4, v1, v49
	v_mul_f32_e32 v97, v61, v90
	v_fmac_f32_e32 v4, v2, v50
	v_mul_f32_e32 v98, v62, v90
	v_fmac_f32_e32 v4, v3, v51
	v_mul_f32_e32 v99, v63, v90
	v_fmac_f32_e32 v96, v0, v52
	v_fmac_f32_e32 v97, v1, v53
	v_add_f32_dpp v4, v4, v4 quad_perm:[1,0,3,2] row_mask:0xf bank_mask:0xf bound_ctrl:1
	v_fmac_f32_e32 v98, v2, v54
	v_fmac_f32_e32 v99, v3, v55
	v_add_f32_dpp v4, v4, v4 quad_perm:[2,3,0,1] row_mask:0xf bank_mask:0xf bound_ctrl:1
	ds_read_b128 v[32:35], v118 offset:1280
	ds_read_b128 v[28:31], v118 offset:9472
	v_add_f32_dpp v4, v4, v4 row_ror:4 row_mask:0xf bank_mask:0xf bound_ctrl:1
	ds_read_b128 v[36:39], v118 offset:17664
	ds_read_b128 v[40:43], v118 offset:25856
	v_add_f32_dpp v4, v4, v4 row_ror:8 row_mask:0xf bank_mask:0xf bound_ctrl:1
	ds_read_b128 v[44:47], v118 offset:34048
	v_fma_f32 v0, -v56, v4, v96
	v_fma_f32 v1, -v57, v4, v97
	v_fma_f32 v2, -v58, v4, v98
	v_fma_f32 v3, -v59, v4, v99
	v_mul_f32_e32 v104, v0, v64
	v_fmac_f32_e32 v104, v1, v65
	v_fmac_f32_e32 v104, v2, v66
	v_fmac_f32_e32 v104, v3, v67
	s_waitcnt lgkmcnt(11)
	v_mul_f32_e32 v4, v0, v68
	v_mul_f32_e32 v96, v80, v91
	v_fmac_f32_e32 v4, v1, v69
	v_mul_f32_e32 v97, v81, v91
	v_fmac_f32_e32 v4, v2, v70
	v_mul_f32_e32 v98, v82, v91
	v_fmac_f32_e32 v4, v3, v71
	v_mul_f32_e32 v99, v83, v91
	v_fmac_f32_e32 v96, v0, v72
	v_fmac_f32_e32 v97, v1, v73
	v_add_f32_dpp v4, v4, v4 quad_perm:[1,0,3,2] row_mask:0xf bank_mask:0xf bound_ctrl:1
	v_fmac_f32_e32 v98, v2, v74
	v_fmac_f32_e32 v99, v3, v75
	v_add_f32_dpp v4, v4, v4 quad_perm:[2,3,0,1] row_mask:0xf bank_mask:0xf bound_ctrl:1
	ds_read_b128 v[52:55], v118 offset:1536
	ds_read_b128 v[48:51], v118 offset:9728
	v_add_f32_dpp v4, v4, v4 row_ror:4 row_mask:0xf bank_mask:0xf bound_ctrl:1
	ds_read_b128 v[56:59], v118 offset:17920
	ds_read_b128 v[60:63], v118 offset:26112
	v_add_f32_dpp v4, v4, v4 row_ror:8 row_mask:0xf bank_mask:0xf bound_ctrl:1
	ds_read_b128 v[64:67], v118 offset:34304
	v_fma_f32 v0, -v76, v4, v96
	v_fma_f32 v1, -v77, v4, v97
	v_fma_f32 v2, -v78, v4, v98
	v_fma_f32 v3, -v79, v4, v99
	v_mul_f32_e32 v105, v0, v84
	v_fmac_f32_e32 v105, v1, v85
	v_fmac_f32_e32 v105, v2, v86
	v_fmac_f32_e32 v105, v3, v87
	s_waitcnt lgkmcnt(10)
	v_mul_f32_e32 v4, v0, v8
	v_mul_f32_e32 v96, v20, v92
	v_fmac_f32_e32 v4, v1, v9
	v_mul_f32_e32 v97, v21, v92
	v_fmac_f32_e32 v4, v2, v10
	v_mul_f32_e32 v98, v22, v92
	v_fmac_f32_e32 v4, v3, v11
	v_mul_f32_e32 v99, v23, v92
	v_fmac_f32_e32 v96, v0, v12
	v_fmac_f32_e32 v97, v1, v13
	v_add_f32_dpp v4, v4, v4 quad_perm:[1,0,3,2] row_mask:0xf bank_mask:0xf bound_ctrl:1
	v_fmac_f32_e32 v98, v2, v14
	v_fmac_f32_e32 v99, v3, v15
	v_add_f32_dpp v4, v4, v4 quad_perm:[2,3,0,1] row_mask:0xf bank_mask:0xf bound_ctrl:1
	ds_read_b128 v[72:75], v118 offset:1792
	ds_read_b128 v[68:71], v118 offset:9984
	v_add_f32_dpp v4, v4, v4 row_ror:4 row_mask:0xf bank_mask:0xf bound_ctrl:1
	ds_read_b128 v[76:79], v118 offset:18176
	ds_read_b128 v[80:83], v118 offset:26368
	v_add_f32_dpp v4, v4, v4 row_ror:8 row_mask:0xf bank_mask:0xf bound_ctrl:1
	ds_read_b128 v[84:87], v118 offset:34560
	v_fma_f32 v0, -v16, v4, v96
	v_fma_f32 v1, -v17, v4, v97
	v_fma_f32 v2, -v18, v4, v98
	v_fma_f32 v3, -v19, v4, v99
	v_mul_f32_e32 v106, v0, v24
	v_fmac_f32_e32 v106, v1, v25
	v_fmac_f32_e32 v106, v2, v26
	v_fmac_f32_e32 v106, v3, v27
	s_waitcnt lgkmcnt(10)
	v_mul_f32_e32 v4, v0, v28
	v_mul_f32_e32 v96, v40, v93
	v_fmac_f32_e32 v4, v1, v29
	v_mul_f32_e32 v97, v41, v93
	v_fmac_f32_e32 v4, v2, v30
	v_mul_f32_e32 v98, v42, v93
	v_fmac_f32_e32 v4, v3, v31
	v_mul_f32_e32 v99, v43, v93
	v_fmac_f32_e32 v96, v0, v32
	v_fmac_f32_e32 v97, v1, v33
	v_add_f32_dpp v4, v4, v4 quad_perm:[1,0,3,2] row_mask:0xf bank_mask:0xf bound_ctrl:1
	v_fmac_f32_e32 v98, v2, v34
	v_fmac_f32_e32 v99, v3, v35
	v_add_f32_dpp v4, v4, v4 quad_perm:[2,3,0,1] row_mask:0xf bank_mask:0xf bound_ctrl:1
	ds_read_b128 v[12:15], v118 offset:2048
	ds_read_b128 v[8:11], v118 offset:10240
	v_add_f32_dpp v4, v4, v4 row_ror:4 row_mask:0xf bank_mask:0xf bound_ctrl:1
	ds_read_b128 v[16:19], v118 offset:18432
	ds_read_b128 v[20:23], v118 offset:26624
	v_add_f32_dpp v4, v4, v4 row_ror:8 row_mask:0xf bank_mask:0xf bound_ctrl:1
	ds_read_b128 v[24:27], v118 offset:34816
	ds_read_b128 v[88:91], v119 offset:32
	v_cndmask_b32_e64 v110, v103, v102, s[78:79]
	v_cndmask_b32_e64 v112, v105, v104, s[78:79]
	v_cndmask_b32_e64 v111, v102, v103, s[78:79]
	v_cndmask_b32_e64 v113, v104, v105, s[78:79]
	v_fma_f32 v0, -v36, v4, v96
	v_fma_f32 v1, -v37, v4, v97
	v_fma_f32 v2, -v38, v4, v98
	v_fma_f32 v3, -v39, v4, v99
	v_mul_f32_e32 v107, v0, v44
	v_fmac_f32_e32 v107, v1, v45
	v_fmac_f32_e32 v107, v2, v46
	v_fmac_f32_e32 v107, v3, v47
	s_waitcnt lgkmcnt(11)
	v_mul_f32_e32 v4, v0, v48
	v_mul_f32_e32 v96, v60, v94
	v_fmac_f32_e32 v4, v1, v49
	v_mul_f32_e32 v97, v61, v94
	v_fmac_f32_e32 v4, v2, v50
	v_mul_f32_e32 v98, v62, v94
	v_fmac_f32_e32 v4, v3, v51
	v_mul_f32_e32 v99, v63, v94
	v_fmac_f32_e32 v96, v0, v52
	v_fmac_f32_e32 v97, v1, v53
	v_add_f32_dpp v4, v4, v4 quad_perm:[1,0,3,2] row_mask:0xf bank_mask:0xf bound_ctrl:1
	v_fmac_f32_e32 v98, v2, v54
	v_fmac_f32_e32 v99, v3, v55
	v_add_f32_dpp v4, v4, v4 quad_perm:[2,3,0,1] row_mask:0xf bank_mask:0xf bound_ctrl:1
	ds_read_b128 v[32:35], v118 offset:2304
	ds_read_b128 v[28:31], v118 offset:10496
	v_add_f32_dpp v4, v4, v4 row_ror:4 row_mask:0xf bank_mask:0xf bound_ctrl:1
	ds_read_b128 v[36:39], v118 offset:18688
	ds_read_b128 v[40:43], v118 offset:26880
	v_add_f32_dpp v4, v4, v4 row_ror:8 row_mask:0xf bank_mask:0xf bound_ctrl:1
	ds_read_b128 v[44:47], v118 offset:35072
	v_add_f32_dpp v114, v110, v111 quad_perm:[1,0,3,2] row_mask:0xf bank_mask:0xf bound_ctrl:1
	v_add_f32_dpp v115, v112, v113 quad_perm:[1,0,3,2] row_mask:0xf bank_mask:0xf bound_ctrl:1
	v_fma_f32 v0, -v56, v4, v96
	v_fma_f32 v1, -v57, v4, v97
	v_fma_f32 v2, -v58, v4, v98
	v_fma_f32 v3, -v59, v4, v99
	v_mul_f32_e32 v108, v0, v64
	v_fmac_f32_e32 v108, v1, v65
	v_fmac_f32_e32 v108, v2, v66
	v_fmac_f32_e32 v108, v3, v67
	v_cndmask_b32_e64 v116, v115, v114, s[80:81]
	v_cndmask_b32_e64 v117, v114, v115, s[80:81]
	s_waitcnt lgkmcnt(11)
	v_mul_f32_e32 v4, v0, v68
	v_mul_f32_e32 v96, v80, v95
	v_fmac_f32_e32 v4, v1, v69
	v_mul_f32_e32 v97, v81, v95
	v_fmac_f32_e32 v4, v2, v70
	v_mul_f32_e32 v98, v82, v95
	v_fmac_f32_e32 v4, v3, v71
	v_mul_f32_e32 v99, v83, v95
	v_fmac_f32_e32 v96, v0, v72
	v_fmac_f32_e32 v97, v1, v73
	v_add_f32_dpp v4, v4, v4 quad_perm:[1,0,3,2] row_mask:0xf bank_mask:0xf bound_ctrl:1
	v_fmac_f32_e32 v98, v2, v74
	v_fmac_f32_e32 v99, v3, v75
	v_add_f32_dpp v4, v4, v4 quad_perm:[2,3,0,1] row_mask:0xf bank_mask:0xf bound_ctrl:1
	ds_read_b128 v[52:55], v118 offset:2560
	ds_read_b128 v[48:51], v118 offset:10752
	v_add_f32_dpp v4, v4, v4 row_ror:4 row_mask:0xf bank_mask:0xf bound_ctrl:1
	ds_read_b128 v[56:59], v118 offset:18944
	ds_read_b128 v[60:63], v118 offset:27136
	v_add_f32_dpp v4, v4, v4 row_ror:8 row_mask:0xf bank_mask:0xf bound_ctrl:1
	ds_read_b128 v[64:67], v118 offset:35328
	v_fma_f32 v0, -v76, v4, v96
	v_fma_f32 v1, -v77, v4, v97
	v_fma_f32 v2, -v78, v4, v98
	v_fma_f32 v3, -v79, v4, v99
	v_mul_f32_e32 v109, v0, v84
	v_fmac_f32_e32 v109, v1, v85
	v_fmac_f32_e32 v109, v2, v86
	v_fmac_f32_e32 v109, v3, v87
	v_add_f32_dpp v114, v116, v117 quad_perm:[2,3,0,1] row_mask:0xf bank_mask:0xf bound_ctrl:1
	v_add_u32_e32 v118, 0x800, v118
	v_add_u32_e32 v119, 32, v119
	v_add_f32_dpp v114, v114, v114 row_ror:4 row_mask:0xf bank_mask:0xf bound_ctrl:1
	s_cmp_eq_u32 s74, 1
	s_cbranch_scc0 .Lsn_nostore
	global_store_dwordx4 v169, v[0:3], s[68:69]
	v_add_u32_e32 v169, 0x200000, v169
.Lsn_nostore:
	v_cndmask_b32_e64 v110, v107, v106, s[78:79]
	v_cndmask_b32_e64 v112, v109, v108, s[78:79]
	v_add_f32_dpp v114, v114, v114 row_ror:8 row_mask:0xf bank_mask:0xf bound_ctrl:1
	v_cndmask_b32_e64 v111, v106, v107, s[78:79]
	v_cndmask_b32_e64 v113, v108, v109, s[78:79]
	ds_write_b32 v120, v114
	v_add_f32_dpp v115, v110, v111 quad_perm:[1,0,3,2] row_mask:0xf bank_mask:0xf bound_ctrl:1
	v_add_f32_dpp v116, v112, v113 quad_perm:[1,0,3,2] row_mask:0xf bank_mask:0xf bound_ctrl:1
	v_cndmask_b32_e64 v110, v116, v115, s[80:81]
	v_cndmask_b32_e64 v111, v115, v116, s[80:81]
	s_sub_i32 s73, s73, 1
	s_cmp_gt_i32 s73, 0
	v_add_f32_dpp v112, v110, v111 quad_perm:[2,3,0,1] row_mask:0xf bank_mask:0xf bound_ctrl:1
	s_nop 1
	v_add_f32_dpp v112, v112, v112 row_ror:4 row_mask:0xf bank_mask:0xf bound_ctrl:1
	s_nop 1
	v_add_f32_dpp v112, v112, v112 row_ror:8 row_mask:0xf bank_mask:0xf bound_ctrl:1
	ds_write_b32 v120, v112 offset:512
	v_add_u32_e32 v120, 0x400, v120
	s_cbranch_scc1 .Lsn_iter
	s_cmp_eq_u32 s72, 64
	s_cbranch_scc0 .Lsn_noB
	global_store_dwordx4 v167, v[0:3], s[70:71]
.Lsn_noB:
	s_cmp_ge_i32 s75, 69
	s_cbranch_scc1 .Lsn_noC
	s_waitcnt vmcnt(0)
	v_mov_b32_e32 v148, v188
	v_mov_b32_e32 v149, v189
	v_mov_b32_e32 v150, v190
	v_mov_b32_e32 v151, v191
	v_mov_b32_e32 v152, v192
	v_mov_b32_e32 v153, v193
	v_mov_b32_e32 v154, v194
	v_mov_b32_e32 v155, v195
	v_mov_b32_e32 v156, v196
	v_mov_b32_e32 v157, v197
	v_mov_b32_e32 v158, v198
	v_mov_b32_e32 v159, v199
	v_mov_b32_e32 v160, v200
	v_mov_b32_e32 v161, v201
	v_mov_b32_e32 v162, v202
	v_mov_b32_e32 v163, v203
	v_lshlrev_b32_e32 v8, 16, v126
	v_and_b32_e32 v9, 0xffff0000, v126
	v_lshlrev_b32_e32 v10, 16, v127
	v_and_b32_e32 v11, 0xffff0000, v127
	v_lshlrev_b32_e32 v12, 16, v128
	v_and_b32_e32 v13, 0xffff0000, v128
	v_lshlrev_b32_e32 v14, 16, v129
	v_and_b32_e32 v15, 0xffff0000, v129
	v_lshlrev_b32_e32 v16, 16, v130
	v_and_b32_e32 v17, 0xffff0000, v130
	v_lshlrev_b32_e32 v18, 16, v131
	v_and_b32_e32 v19, 0xffff0000, v131
	v_lshlrev_b32_e32 v20, 16, v132
	v_and_b32_e32 v21, 0xffff0000, v132
	v_lshlrev_b32_e32 v22, 16, v133
	v_and_b32_e32 v23, 0xffff0000, v133
	v_lshlrev_b32_e32 v24, 16, v134
	v_and_b32_e32 v25, 0xffff0000, v134
	v_lshlrev_b32_e32 v26, 16, v135
	v_and_b32_e32 v27, 0xffff0000, v135
	v_pk_mul_f32 v[28:29], v[8:9], v[136:137]
	v_pk_mul_f32 v[30:31], v[10:11], v[138:139]
	v_pk_mul_f32 v[32:33], v[28:29], v[28:29]
	v_pk_fma_f32 v[32:33], v[30:31], v[30:31], v[32:33]
	v_add_f32_e32 v34, v32, v33
	v_add_f32_e32 v36, -1.0, v16
	v_add_f32_e32 v37, -1.0, v17
	v_add_f32_e32 v38, -1.0, v18
	v_add_f32_e32 v39, -1.0, v19
	v_add_f32_dpp v34, v34, v34 quad_perm:[1,0,3,2] row_mask:0xf bank_mask:0xf bound_ctrl:1
	v_fma_f32 v36, v36, v140, 1.0
	v_fma_f32 v37, v37, v141, 1.0
	v_fma_f32 v38, v38, v142, 1.0
	v_fma_f32 v39, v39, v143, 1.0
	v_add_f32_dpp v34, v34, v34 quad_perm:[2,3,0,1] row_mask:0xf bank_mask:0xf bound_ctrl:1
	v_pk_mul_f32 v[40:41], v[8:9], v[36:37]
	v_pk_mul_f32 v[42:43], v[10:11], v[38:39]
	v_add_f32_dpp v34, v34, v34 row_ror:4 row_mask:0xf bank_mask:0xf bound_ctrl:1
	v_mul_f32_e32 v44, 0x3fb8aa3b, v20
	v_mul_f32_e32 v45, 0x3fb8aa3b, v21
	v_mul_f32_e32 v46, 0x3fb8aa3b, v22
	v_mul_f32_e32 v47, 0x3fb8aa3b, v23
	v_add_f32_dpp v34, v34, v34 row_ror:8 row_mask:0xf bank_mask:0xf bound_ctrl:1
	v_exp_f32_e32 v44, v44
	v_exp_f32_e32 v45, v45
	v_exp_f32_e32 v46, v46
	v_exp_f32_e32 v47, v47
	v_sqrt_f32_e32 v35, v34
	v_pk_mul_f32 v[52:53], v[12:13], v[40:41]
	v_pk_mul_f32 v[54:55], v[14:15], v[42:43]
	v_max_f32_e32 v35, 0x2b8cbccc, v35
	v_rcp_f32_e32 v35, v35
	v_pk_mul_f32 v[52:53], v[52:53], v[144:145]
	v_pk_fma_f32 v[52:53], v[54:55], v[146:147], v[52:53]
	v_pk_mul_f32 v[28:29], v[28:29], v[34:35] op_sel:[0,1]
	v_pk_mul_f32 v[30:31], v[30:31], v[34:35] op_sel:[0,1]
	v_add_f32_e32 v56, v52, v53
	v_pk_mul_f32 v[48:49], v[28:29], v[16:17]
	v_pk_mul_f32 v[50:51], v[30:31], v[18:19]
	v_add_f32_dpp v56, v56, v56 quad_perm:[1,0,3,2] row_mask:0xf bank_mask:0xf bound_ctrl:1
	s_and_b32 s76, s75, 1
	s_mul_i32 s76, s76, 45056
	v_add_f32_dpp v56, v56, v56 quad_perm:[2,3,0,1] row_mask:0xf bank_mask:0xf bound_ctrl:1
	v_add_u32_e32 v57, s76, v123
	v_add_u32_e32 v58, s76, v124
	v_add_f32_dpp v56, v56, v56 row_ror:4 row_mask:0xf bank_mask:0xf bound_ctrl:1
	ds_write_b128 v57, v[44:47] offset:0
	ds_write_b128 v57, v[28:31] offset:8192
	v_add_f32_dpp v56, v56, v56 row_ror:8 row_mask:0xf bank_mask:0xf bound_ctrl:1
	ds_write_b128 v57, v[48:51] offset:16384
	ds_write_b128 v57, v[40:43] offset:24576
	ds_write_b128 v57, v[12:15] offset:32768
	s_and_saveexec_b64 s[76:77], s[82:83]
	ds_write_b32 v58, v24 offset:0
	ds_write_b32 v58, v25 offset:128
	ds_write_b32 v58, v26 offset:256
	ds_write_b32 v58, v27 offset:384
	s_mov_b64 exec, s[76:77]
	s_and_b64 s[90:91], s[84:85], s[86:87]
	v_lshlrev_b32_e32 v59, 6, v170
	s_and_saveexec_b64 s[76:77], s[90:91]
	s_cbranch_execz .Lsn_nocb
	s_lshr_b32 s92, s14, 1
	s_and_b32 s92, s92, 15
	s_lshl_b32 s92, s92, 2
	v_add_u32_e32 v59, s92, v59
	global_store_dword v59, v56, s[64:65]
.Lsn_nocb:
	s_mov_b64 exec, s[76:77]
.Lsn_noC:
	s_cmp_lt_i32 s72, 1
	s_cbranch_scc1 .Lsn_noD
	s_sub_i32 s76, s72, 1
	s_cmp_ge_i32 s76, 65
	s_cbranch_scc1 .Lsn_ya_s
	s_lshl_b32 s77, s76, 5
	v_add_u32_e32 v174, s77, v121
	s_movk_i32 s92, 0x810
	v_cmp_gt_u32_e64 s[90:91], s92, v174
	v_add_u32_e32 v174, s88, v174
	s_mov_b64 s[92:93], s[60:61]
	s_branch .Lsn_ya_c
.Lsn_ya_s:
	s_sub_i32 s77, s76, 65
	s_lshl_b32 s77, s77, 8
	s_add_i32 s77, s77, s89
	v_add_u32_e32 v174, s77, v168
	s_mov_b64 s[90:91], -1
	s_mov_b64 s[92:93], s[62:63]
.Lsn_ya_c:
	s_and_b32 s77, s76, 1
	s_lshl_b32 s77, s77, 12
	v_add_u32_e32 v10, s77, v125
	ds_read_b64 v[8:9], v10
	v_lshl_add_u32 v11, v174, 11, v166
	s_waitcnt lgkmcnt(0)
	v_cvt_pk_bf16_f32 v8, v8, v9
	s_and_saveexec_b64 s[76:77], s[90:91]
	global_store_dword v11, v8, s[92:93]
	s_mov_b64 exec, s[76:77]
.Lsn_noD:
	s_waitcnt lgkmcnt(0)
	s_barrier
	s_add_i32 s72, s72, 1
	s_cmp_lt_i32 s72, 69
	s_cbranch_scc1 .Lsn_chunk
	s_mov_b32 s76, 68
	s_cmp_ge_i32 s76, 65
	s_cbranch_scc1 .Lsn_yb_s
	s_lshl_b32 s77, s76, 5
	v_add_u32_e32 v174, s77, v121
	s_movk_i32 s92, 0x810
	v_cmp_gt_u32_e64 s[90:91], s92, v174
	v_add_u32_e32 v174, s88, v174
	s_mov_b64 s[92:93], s[60:61]
	s_branch .Lsn_yb_c

.Lsn_fin:
	s_waitcnt vmcnt(0) lgkmcnt(0)
	s_barrier
	v_readlane_b32 s50, v175, 0
	v_readlane_b32 s51, v175, 1
	v_readlane_b32 s52, v175, 2
	v_readlane_b32 s53, v175, 3
	v_readlane_b32 s54, v175, 4
	v_readlane_b32 s55, v175, 5
	v_readlane_b32 s56, v175, 6
	v_readlane_b32 s57, v175, 7
	v_readlane_b32 s58, v175, 8
	v_readlane_b32 s59, v175, 9
	v_readlane_b32 s60, v175, 10
	v_readlane_b32 s61, v175, 11
	v_readlane_b32 s62, v175, 12
	v_readlane_b32 s63, v175, 13
	v_readlane_b32 s64, v175, 14
	v_readlane_b32 s65, v175, 15
	v_readlane_b32 s66, v175, 16
	v_readlane_b32 s67, v175, 17
	v_readlane_b32 s68, v175, 18
	v_readlane_b32 s69, v175, 19
	v_readlane_b32 s70, v175, 20
	v_readlane_b32 s71, v175, 21
	v_readlane_b32 s72, v175, 22
	v_readlane_b32 s73, v175, 23
	v_readlane_b32 s74, v175, 24
	v_readlane_b32 s75, v175, 25
	v_readlane_b32 s76, v175, 26
	v_readlane_b32 s77, v175, 27
	v_readlane_b32 s78, v175, 28
	v_readlane_b32 s79, v175, 29
	v_readlane_b32 s80, v175, 30
	v_readlane_b32 s81, v175, 31
	v_readlane_b32 s82, v175, 32
	v_readlane_b32 s83, v175, 33
	v_readlane_b32 s84, v175, 34
	v_readlane_b32 s85, v175, 35
	v_readlane_b32 s86, v175, 36
	v_readlane_b32 s87, v175, 37
	v_readlane_b32 s88, v175, 38
	v_readlane_b32 s89, v175, 39
	v_readlane_b32 s90, v175, 40
	v_readlane_b32 s91, v175, 41
	v_readlane_b32 s92, v175, 42
	v_readlane_b32 s93, v175, 43
	s_nop 4
	s_branch .LBB0_389
